# dense attention loop: last PV MFMA of each sub-step issued after the sub-step barrier (barrier wait overlaps MFMA execution)
# speedup vs baseline: 1.0706x; 1.0049x over previous
; template <int DV, int NK, int MODE, bool FIXM, int GRP>
; DI void attn_job(char* lds_wg, const AttnJob& J) {
;     ...
;       if (FIXM) {
;         const float nm = -J.m_init;
; #pragma unroll
;         for (int i = 0; i < 16; ++i) { sA[i] = __builtin_amdgcn_exp2f(fmaf(sA[i], C, nm)); sB[i] = __builtin_amdgcn_exp2f(fmaf(sB[i], C, nm)); l += sA[i] + sB[i]; }
;       } else {
;       float mx = sA[0];
; #pragma unroll
;       for (int i = 1; i < 16; ++i) mx = fmaxf(mx, sA[i]);
; #pragma unroll
;       for (int i = 0; i < 16; ++i) mx = fmaxf(mx, sB[i]);
;       mx = swapmax(mx);
;       const float mn = fmaxf(m, mx * C);
;       const float alpha = __builtin_amdgcn_exp2f(m - mn);
;       m = mn;
;       float ps = 0.f;
; #pragma unroll
;       for (int i = 0; i < 16; ++i) { sA[i] = __builtin_amdgcn_exp2f(fmaf(sA[i], C, -mn)); sB[i] = __builtin_amdgcn_exp2f(fmaf(sB[i], C, -mn)); ps += sA[i] + sB[i]; }
;       l = l * alpha + ps;
; #pragma unroll
;       for (int d = 0; d < NDV; ++d)
; #pragma unroll
;         for (int i = 0; i < 16; ++i) O[d][i] *= alpha;
;       }
;       bf16x8 pf[4];
;       { u32x4 w;
;         w.x = cvtpk(sA[0], sA[1]); w.y = cvtpk(sA[2], sA[3]); w.z = cvtpk(sA[4], sA[5]); w.w = cvtpk(sA[6], sA[7]); pf[0] = __builtin_bit_cast(bf16x8, w);
;         w.x = cvtpk(sA[8], sA[9]); w.y = cvtpk(sA[10], sA[11]); w.z = cvtpk(sA[12], sA[13]); w.w = cvtpk(sA[14], sA[15]); pf[1] = __builtin_bit_cast(bf16x8, w);
;         w.x = cvtpk(sB[0], sB[1]); w.y = cvtpk(sB[2], sB[3]); w.z = cvtpk(sB[4], sB[5]); w.w = cvtpk(sB[6], sB[7]); pf[2] = __builtin_bit_cast(bf16x8, w);
;         w.x = cvtpk(sB[8], sB[9]); w.y = cvtpk(sB[10], sB[11]); w.z = cvtpk(sB[12], sB[13]); w.w = cvtpk(sB[14], sB[15]); pf[3] = __builtin_bit_cast(bf16x8, w); }
;       const char* Vl = lds + stage * 32768 + NK * 8192 + vrd;
;       if (FIXM) {
;         bf16x8 vf[4][NDV];
; #pragma unroll
;         for (int ks = 0; ks < 4; ++ks) {
; #pragma unroll
;           for (int d = 0; d < NDV; ++d) {
;             const s16x4 lo = __builtin_amdgcn_ds_read_tr16_b64_v4i16((LAS s16x4*)(Vl + ks * 2 * NDV * 512 + d * 512));
;             const s16x4 hi = __builtin_amdgcn_ds_read_tr16_b64_v4i16((LAS s16x4*)(Vl + ks * 2 * NDV * 512 + d * 512 + 256));
;             vf[ks][d] = __builtin_shufflevector(lo, hi, 0, 1, 2, 3, 4, 5, 6, 7);
;           }
;         }
; #pragma unroll
.Lds0_sk0:
	v_add_f32_e32 v164, v56, v164
	v_add_f32_e32 v164, v57, v164
	s_waitcnt lgkmcnt(12)
	v_mfma_f32_32x32x16_bf16 v[18:33], v[168:171], v[152:155], v[18:33]
	v_cvt_pk_bf16_f32 v156, v58, v59
	v_cvt_pk_bf16_f32 v157, v60, v61
	v_cvt_pk_bf16_f32 v158, v62, v63
	v_cvt_pk_bf16_f32 v159, v64, v65
	v_add_f32_e32 v115, v58, v115
	v_add_f32_e32 v115, v59, v115
	s_waitcnt lgkmcnt(10)
	v_mfma_f32_32x32x16_bf16 v[2:17], v[172:175], v[152:155], v[2:17]
	v_add_f32_e32 v164, v60, v164
	v_add_f32_e32 v164, v61, v164
	v_add_f32_e32 v164, v62, v164
	v_add_f32_e32 v164, v63, v164
	v_add_f32_e32 v164, v64, v164
	v_add_f32_e32 v164, v65, v164
	s_waitcnt lgkmcnt(8)
	v_mfma_f32_32x32x16_bf16 v[18:33], v[176:179], v[156:159], v[18:33]
	v_exp_f32_e32 v34, v34
	v_exp_f32_e32 v35, v35
	v_exp_f32_e32 v36, v36
	v_exp_f32_e32 v37, v37
	s_waitcnt lgkmcnt(6)
	v_mfma_f32_32x32x16_bf16 v[2:17], v[180:183], v[156:159], v[2:17]
	ds_read_b64_tr_b16 v[168:169], v98 offset:12288
	ds_read_b64_tr_b16 v[170:171], v98 offset:12544
	ds_read_b64_tr_b16 v[172:173], v98 offset:12800
	ds_read_b64_tr_b16 v[174:175], v98 offset:13056
	ds_read_b64_tr_b16 v[176:177], v98 offset:14336
	ds_read_b64_tr_b16 v[178:179], v98 offset:14592
	ds_read_b64_tr_b16 v[180:181], v98 offset:14848
	ds_read_b64_tr_b16 v[182:183], v98 offset:15104
	v_exp_f32_e32 v38, v38
	v_exp_f32_e32 v39, v39
	v_exp_f32_e32 v40, v40
	v_exp_f32_e32 v41, v41
	s_waitcnt lgkmcnt(13)
	v_mfma_f32_32x32x16_bf16 v[50:65], v[106:109], v[66:69], 0
	v_cvt_pk_bf16_f32 v160, v34, v35
	v_cvt_pk_bf16_f32 v161, v36, v37
	v_cvt_pk_bf16_f32 v162, v38, v39
	v_cvt_pk_bf16_f32 v163, v40, v41
	v_add_f32_e32 v115, v34, v115
	v_add_f32_e32 v115, v35, v115
	s_waitcnt lgkmcnt(12)
	v_mfma_f32_32x32x16_bf16 v[50:65], v[110:113], v[70:73], v[50:65]
	v_exp_f32_e32 v42, v42
	v_exp_f32_e32 v43, v43
	v_exp_f32_e32 v44, v44
	v_exp_f32_e32 v45, v45
	v_add_f32_e32 v164, v36, v164
	v_add_f32_e32 v164, v37, v164
	s_waitcnt lgkmcnt(11)
	v_mfma_f32_32x32x16_bf16 v[50:65], v[120:123], v[74:77], v[50:65]
	v_exp_f32_e32 v46, v46
	v_exp_f32_e32 v47, v47
	v_exp_f32_e32 v48, v48
	v_exp_f32_e32 v49, v49
	v_add_f32_e32 v115, v38, v115
	v_add_f32_e32 v115, v39, v115
	s_waitcnt lgkmcnt(10)
	v_mfma_f32_32x32x16_bf16 v[50:65], v[124:127], v[78:81], v[50:65]
	v_cvt_pk_bf16_f32 v184, v42, v43
	v_cvt_pk_bf16_f32 v185, v44, v45
	v_cvt_pk_bf16_f32 v186, v46, v47
	v_cvt_pk_bf16_f32 v187, v48, v49
	v_add_f32_e32 v164, v40, v164
	v_add_f32_e32 v164, v41, v164
	s_waitcnt lgkmcnt(6)
	v_mfma_f32_32x32x16_bf16 v[18:33], v[168:171], v[160:163], v[18:33]
	v_add_f32_e32 v115, v42, v115
	v_add_f32_e32 v115, v43, v115
	v_add_f32_e32 v115, v44, v115
	v_add_f32_e32 v115, v45, v115
	s_waitcnt lgkmcnt(4)
	v_mfma_f32_32x32x16_bf16 v[2:17], v[172:175], v[160:163], v[2:17]
	v_add_f32_e32 v164, v46, v164
	v_add_f32_e32 v164, v47, v164
	v_add_f32_e32 v164, v48, v164
	v_add_f32_e32 v164, v49, v164
	s_waitcnt lgkmcnt(2)
	v_mfma_f32_32x32x16_bf16 v[18:33], v[176:179], v[184:187], v[18:33]
	s_waitcnt lgkmcnt(0)
	s_waitcnt lgkmcnt(0)
	s_barrier
	v_mfma_f32_32x32x16_bf16 v[2:17], v[180:183], v[184:187], v[2:17]
	s_add_i32 s38, s38, 1
	s_cmp_ge_u32 s38, s96
	s_cbranch_scc1 .Lds0_done
	ds_read_b128 v[106:109], v0 offset:32768
	ds_read_b128 v[110:113], v102 offset:32768
	ds_read_b128 v[120:123], v103 offset:32768
	ds_read_b128 v[124:127], v104 offset:32768
	ds_read_b64_tr_b16 v[168:169], v98 offset:24576
	ds_read_b64_tr_b16 v[170:171], v98 offset:24832
	ds_read_b64_tr_b16 v[172:173], v98 offset:25088
	ds_read_b64_tr_b16 v[174:175], v98 offset:25344
	ds_read_b64_tr_b16 v[176:177], v98 offset:26624
	ds_read_b64_tr_b16 v[178:179], v98 offset:26880
	ds_read_b64_tr_b16 v[180:181], v98 offset:27136
	ds_read_b64_tr_b16 v[182:183], v98 offset:27392
	v_exp_f32_e32 v136, v136
	v_exp_f32_e32 v137, v137
	v_exp_f32_e32 v138, v138
	v_exp_f32_e32 v139, v139
	v_exp_f32_e32 v140, v140
	v_exp_f32_e32 v141, v141
	v_exp_f32_e32 v142, v142
	v_exp_f32_e32 v143, v143
	s_waitcnt lgkmcnt(11)
	v_mfma_f32_32x32x16_bf16 v[34:49], v[106:109], v[66:69], 0
	v_cvt_pk_bf16_f32 v152, v136, v137
	v_cvt_pk_bf16_f32 v153, v138, v139
	v_cvt_pk_bf16_f32 v154, v140, v141
	v_cvt_pk_bf16_f32 v155, v142, v143
	v_add_f32_e32 v115, v136, v115
	v_add_f32_e32 v115, v137, v115
	s_waitcnt lgkmcnt(10)
	v_mfma_f32_32x32x16_bf16 v[34:49], v[110:113], v[70:73], v[34:49]
	v_exp_f32_e32 v144, v144
	v_exp_f32_e32 v145, v145
	v_exp_f32_e32 v146, v146
	v_exp_f32_e32 v147, v147
	v_add_f32_e32 v164, v138, v164
	v_add_f32_e32 v164, v139, v164
	s_waitcnt lgkmcnt(9)
	v_mfma_f32_32x32x16_bf16 v[34:49], v[120:123], v[74:77], v[34:49]
	v_exp_f32_e32 v148, v148
	v_exp_f32_e32 v149, v149
	v_exp_f32_e32 v150, v150
	v_exp_f32_e32 v151, v151
	v_add_f32_e32 v115, v140, v115
	v_add_f32_e32 v115, v141, v115
	s_waitcnt lgkmcnt(8)
	v_mfma_f32_32x32x16_bf16 v[34:49], v[124:127], v[78:81], v[34:49]
	ds_read_b128 v[106:109], v0 offset:36864
	ds_read_b128 v[110:113], v102 offset:36864
	ds_read_b128 v[120:123], v103 offset:36864
	ds_read_b128 v[124:127], v104 offset:36864
	s_waitcnt vmcnt(0)
	ds_write_b128 v100, v[82:85] offset:0
	ds_write_b128 v165, v[86:89] offset:8192
	s_add_i32 s39, s38, 3
	s_cmp_lt_u32 s39, s96
	s_cbranch_scc0 .Lds0_sk1
	global_load_dwordx4 v[82:85], v[92:93], off offset:1024
	global_load_dwordx4 v[86:89], v[90:91], off offset:1280
	v_lshl_add_u64 v[92:93], v[92:93], 0, s[70:71]
	v_lshl_add_u64 v[90:91], v[90:91], 0, s[70:71]
; template <int DV, int NK, int MODE, bool FIXM, int GRP>
; DI void attn_job(char* lds_wg, const AttnJob& J) {
;     ...
;       if (FIXM) {
;         const float nm = -J.m_init;
; #pragma unroll
;         for (int i = 0; i < 16; ++i) { sA[i] = __builtin_amdgcn_exp2f(fmaf(sA[i], C, nm)); sB[i] = __builtin_amdgcn_exp2f(fmaf(sB[i], C, nm)); l += sA[i] + sB[i]; }
;       } else {
;       float mx = sA[0];
; #pragma unroll
;       for (int i = 1; i < 16; ++i) mx = fmaxf(mx, sA[i]);
; #pragma unroll
;       for (int i = 0; i < 16; ++i) mx = fmaxf(mx, sB[i]);
;       mx = swapmax(mx);
;       const float mn = fmaxf(m, mx * C);
;       const float alpha = __builtin_amdgcn_exp2f(m - mn);
;       m = mn;
;       float ps = 0.f;
; #pragma unroll
;       for (int i = 0; i < 16; ++i) { sA[i] = __builtin_amdgcn_exp2f(fmaf(sA[i], C, -mn)); sB[i] = __builtin_amdgcn_exp2f(fmaf(sB[i], C, -mn)); ps += sA[i] + sB[i]; }
;       l = l * alpha + ps;
; #pragma unroll
;       for (int d = 0; d < NDV; ++d)
; #pragma unroll
;         for (int i = 0; i < 16; ++i) O[d][i] *= alpha;
;       }
;       bf16x8 pf[4];
;       { u32x4 w;
;         w.x = cvtpk(sA[0], sA[1]); w.y = cvtpk(sA[2], sA[3]); w.z = cvtpk(sA[4], sA[5]); w.w = cvtpk(sA[6], sA[7]); pf[0] = __builtin_bit_cast(bf16x8, w);
;         w.x = cvtpk(sA[8], sA[9]); w.y = cvtpk(sA[10], sA[11]); w.z = cvtpk(sA[12], sA[13]); w.w = cvtpk(sA[14], sA[15]); pf[1] = __builtin_bit_cast(bf16x8, w);
;         w.x = cvtpk(sB[0], sB[1]); w.y = cvtpk(sB[2], sB[3]); w.z = cvtpk(sB[4], sB[5]); w.w = cvtpk(sB[6], sB[7]); pf[2] = __builtin_bit_cast(bf16x8, w);
;         w.x = cvtpk(sB[8], sB[9]); w.y = cvtpk(sB[10], sB[11]); w.z = cvtpk(sB[12], sB[13]); w.w = cvtpk(sB[14], sB[15]); pf[3] = __builtin_bit_cast(bf16x8, w); }
;       const char* Vl = lds + stage * 32768 + NK * 8192 + vrd;
;       if (FIXM) {
;         bf16x8 vf[4][NDV];
; #pragma unroll
;         for (int ks = 0; ks < 4; ++ks) {
; #pragma unroll
;           for (int d = 0; d < NDV; ++d) {
;             const s16x4 lo = __builtin_amdgcn_ds_read_tr16_b64_v4i16((LAS s16x4*)(Vl + ks * 2 * NDV * 512 + d * 512));
;             const s16x4 hi = __builtin_amdgcn_ds_read_tr16_b64_v4i16((LAS s16x4*)(Vl + ks * 2 * NDV * 512 + d * 512 + 256));
;             vf[ks][d] = __builtin_shufflevector(lo, hi, 0, 1, 2, 3, 4, 5, 6, 7);
;           }
;         }
; #pragma unroll
.Lds0_sk1:
	v_add_f32_e32 v164, v142, v164
	v_add_f32_e32 v164, v143, v164
	s_waitcnt lgkmcnt(12)
	v_mfma_f32_32x32x16_bf16 v[18:33], v[168:171], v[152:155], v[18:33]
	v_cvt_pk_bf16_f32 v156, v144, v145
	v_cvt_pk_bf16_f32 v157, v146, v147
	v_cvt_pk_bf16_f32 v158, v148, v149
	v_cvt_pk_bf16_f32 v159, v150, v151
	v_add_f32_e32 v115, v144, v115
	v_add_f32_e32 v115, v145, v115
	s_waitcnt lgkmcnt(10)
	v_mfma_f32_32x32x16_bf16 v[2:17], v[172:175], v[152:155], v[2:17]
	v_add_f32_e32 v164, v146, v164
	v_add_f32_e32 v164, v147, v164
	v_add_f32_e32 v164, v148, v164
	v_add_f32_e32 v164, v149, v164
	v_add_f32_e32 v164, v150, v164
	v_add_f32_e32 v164, v151, v164
	s_waitcnt lgkmcnt(8)
	v_mfma_f32_32x32x16_bf16 v[18:33], v[176:179], v[156:159], v[18:33]
	v_exp_f32_e32 v50, v50
	v_exp_f32_e32 v51, v51
	v_exp_f32_e32 v52, v52
	v_exp_f32_e32 v53, v53
	s_waitcnt lgkmcnt(6)
	v_mfma_f32_32x32x16_bf16 v[2:17], v[180:183], v[156:159], v[2:17]
	ds_read_b64_tr_b16 v[168:169], v98 offset:28672
	ds_read_b64_tr_b16 v[170:171], v98 offset:28928
	ds_read_b64_tr_b16 v[172:173], v98 offset:29184
	ds_read_b64_tr_b16 v[174:175], v98 offset:29440
	ds_read_b64_tr_b16 v[176:177], v98 offset:30720
	ds_read_b64_tr_b16 v[178:179], v98 offset:30976
	ds_read_b64_tr_b16 v[180:181], v98 offset:31232
	ds_read_b64_tr_b16 v[182:183], v98 offset:31488
	v_exp_f32_e32 v54, v54
	v_exp_f32_e32 v55, v55
	v_exp_f32_e32 v56, v56
	v_exp_f32_e32 v57, v57
	s_waitcnt lgkmcnt(13)
	v_mfma_f32_32x32x16_bf16 v[136:151], v[106:109], v[66:69], 0
	v_cvt_pk_bf16_f32 v160, v50, v51
	v_cvt_pk_bf16_f32 v161, v52, v53
	v_cvt_pk_bf16_f32 v162, v54, v55
	v_cvt_pk_bf16_f32 v163, v56, v57
	v_add_f32_e32 v115, v50, v115
	v_add_f32_e32 v115, v51, v115
	s_waitcnt lgkmcnt(12)
	v_mfma_f32_32x32x16_bf16 v[136:151], v[110:113], v[70:73], v[136:151]
	v_exp_f32_e32 v58, v58
	v_exp_f32_e32 v59, v59
	v_exp_f32_e32 v60, v60
	v_exp_f32_e32 v61, v61
	v_add_f32_e32 v164, v52, v164
	v_add_f32_e32 v164, v53, v164
	s_waitcnt lgkmcnt(11)
	v_mfma_f32_32x32x16_bf16 v[136:151], v[120:123], v[74:77], v[136:151]
	v_exp_f32_e32 v62, v62
	v_exp_f32_e32 v63, v63
	v_exp_f32_e32 v64, v64
	v_exp_f32_e32 v65, v65
	v_add_f32_e32 v115, v54, v115
	v_add_f32_e32 v115, v55, v115
	s_waitcnt lgkmcnt(10)
	v_mfma_f32_32x32x16_bf16 v[136:151], v[124:127], v[78:81], v[136:151]
	v_cvt_pk_bf16_f32 v184, v58, v59
	v_cvt_pk_bf16_f32 v185, v60, v61
	v_cvt_pk_bf16_f32 v186, v62, v63
	v_cvt_pk_bf16_f32 v187, v64, v65
	v_add_f32_e32 v164, v56, v164
	v_add_f32_e32 v164, v57, v164
	s_waitcnt lgkmcnt(6)
	v_mfma_f32_32x32x16_bf16 v[18:33], v[168:171], v[160:163], v[18:33]
	v_add_f32_e32 v115, v58, v115
	v_add_f32_e32 v115, v59, v115
	v_add_f32_e32 v115, v60, v115
	v_add_f32_e32 v115, v61, v115
	s_waitcnt lgkmcnt(4)
	v_mfma_f32_32x32x16_bf16 v[2:17], v[172:175], v[160:163], v[2:17]
	v_add_f32_e32 v164, v62, v164
	v_add_f32_e32 v164, v63, v164
	v_add_f32_e32 v164, v64, v164
	v_add_f32_e32 v164, v65, v164
	s_waitcnt lgkmcnt(2)
	v_mfma_f32_32x32x16_bf16 v[18:33], v[176:179], v[184:187], v[18:33]
	s_waitcnt lgkmcnt(0)
	s_waitcnt lgkmcnt(0)
	s_barrier
	v_mfma_f32_32x32x16_bf16 v[2:17], v[180:183], v[184:187], v[2:17]
	s_add_i32 s38, s38, 1
	s_cmp_ge_u32 s38, s96
	s_cbranch_scc1 .Lds0_done
	ds_read_b128 v[106:109], v0 offset:0
	ds_read_b128 v[110:113], v102 offset:0
	ds_read_b128 v[120:123], v103 offset:0
	ds_read_b128 v[124:127], v104 offset:0
	ds_read_b64_tr_b16 v[168:169], v98 offset:40960
	ds_read_b64_tr_b16 v[170:171], v98 offset:41216
	ds_read_b64_tr_b16 v[172:173], v98 offset:41472
	ds_read_b64_tr_b16 v[174:175], v98 offset:41728
	ds_read_b64_tr_b16 v[176:177], v98 offset:43008
	ds_read_b64_tr_b16 v[178:179], v98 offset:43264
	ds_read_b64_tr_b16 v[180:181], v98 offset:43520
	ds_read_b64_tr_b16 v[182:183], v98 offset:43776
	v_exp_f32_e32 v34, v34
	v_exp_f32_e32 v35, v35
	v_exp_f32_e32 v36, v36
	v_exp_f32_e32 v37, v37
	v_exp_f32_e32 v38, v38
	v_exp_f32_e32 v39, v39
	v_exp_f32_e32 v40, v40
	v_exp_f32_e32 v41, v41
	s_waitcnt lgkmcnt(11)
	v_mfma_f32_32x32x16_bf16 v[50:65], v[106:109], v[66:69], 0
	v_cvt_pk_bf16_f32 v152, v34, v35
	v_cvt_pk_bf16_f32 v153, v36, v37
	v_cvt_pk_bf16_f32 v154, v38, v39
	v_cvt_pk_bf16_f32 v155, v40, v41
	v_add_f32_e32 v115, v34, v115
	v_add_f32_e32 v115, v35, v115
	s_waitcnt lgkmcnt(10)
	v_mfma_f32_32x32x16_bf16 v[50:65], v[110:113], v[70:73], v[50:65]
	v_exp_f32_e32 v42, v42
	v_exp_f32_e32 v43, v43
	v_exp_f32_e32 v44, v44
	v_exp_f32_e32 v45, v45
	v_add_f32_e32 v164, v36, v164
	v_add_f32_e32 v164, v37, v164
	s_waitcnt lgkmcnt(9)
	v_mfma_f32_32x32x16_bf16 v[50:65], v[120:123], v[74:77], v[50:65]
	v_exp_f32_e32 v46, v46
	v_exp_f32_e32 v47, v47
	v_exp_f32_e32 v48, v48
	v_exp_f32_e32 v49, v49
	v_add_f32_e32 v115, v38, v115
	v_add_f32_e32 v115, v39, v115
	s_waitcnt lgkmcnt(8)
	v_mfma_f32_32x32x16_bf16 v[50:65], v[124:127], v[78:81], v[50:65]
	ds_read_b128 v[106:109], v0 offset:4096
	ds_read_b128 v[110:113], v102 offset:4096
	ds_read_b128 v[120:123], v103 offset:4096
	ds_read_b128 v[124:127], v104 offset:4096
	s_waitcnt vmcnt(0)
	ds_write_b128 v100, v[82:85] offset:16384
	ds_write_b128 v165, v[86:89] offset:24576
	s_add_i32 s39, s38, 3
	s_cmp_lt_u32 s39, s96
	s_cbranch_scc0 .Lds0_sk2
	global_load_dwordx4 v[82:85], v[92:93], off offset:1024
	global_load_dwordx4 v[86:89], v[90:91], off offset:1280
	v_lshl_add_u64 v[92:93], v[92:93], 0, s[70:71]
	v_lshl_add_u64 v[90:91], v[90:91], 0, s[70:71]
; template <int DV, int NK, int MODE, bool FIXM, int GRP>
; DI void attn_job(char* lds_wg, const AttnJob& J) {
;     ...
;       if (FIXM) {
;         const float nm = -J.m_init;
; #pragma unroll
;         for (int i = 0; i < 16; ++i) { sA[i] = __builtin_amdgcn_exp2f(fmaf(sA[i], C, nm)); sB[i] = __builtin_amdgcn_exp2f(fmaf(sB[i], C, nm)); l += sA[i] + sB[i]; }
;       } else {
;       float mx = sA[0];
; #pragma unroll
;       for (int i = 1; i < 16; ++i) mx = fmaxf(mx, sA[i]);
; #pragma unroll
;       for (int i = 0; i < 16; ++i) mx = fmaxf(mx, sB[i]);
;       mx = swapmax(mx);
;       const float mn = fmaxf(m, mx * C);
;       const float alpha = __builtin_amdgcn_exp2f(m - mn);
;       m = mn;
;       float ps = 0.f;
; #pragma unroll
;       for (int i = 0; i < 16; ++i) { sA[i] = __builtin_amdgcn_exp2f(fmaf(sA[i], C, -mn)); sB[i] = __builtin_amdgcn_exp2f(fmaf(sB[i], C, -mn)); ps += sA[i] + sB[i]; }
;       l = l * alpha + ps;
; #pragma unroll
;       for (int d = 0; d < NDV; ++d)
; #pragma unroll
;         for (int i = 0; i < 16; ++i) O[d][i] *= alpha;
;       }
;       bf16x8 pf[4];
;       { u32x4 w;
;         w.x = cvtpk(sA[0], sA[1]); w.y = cvtpk(sA[2], sA[3]); w.z = cvtpk(sA[4], sA[5]); w.w = cvtpk(sA[6], sA[7]); pf[0] = __builtin_bit_cast(bf16x8, w);
;         w.x = cvtpk(sA[8], sA[9]); w.y = cvtpk(sA[10], sA[11]); w.z = cvtpk(sA[12], sA[13]); w.w = cvtpk(sA[14], sA[15]); pf[1] = __builtin_bit_cast(bf16x8, w);
;         w.x = cvtpk(sB[0], sB[1]); w.y = cvtpk(sB[2], sB[3]); w.z = cvtpk(sB[4], sB[5]); w.w = cvtpk(sB[6], sB[7]); pf[2] = __builtin_bit_cast(bf16x8, w);
;         w.x = cvtpk(sB[8], sB[9]); w.y = cvtpk(sB[10], sB[11]); w.z = cvtpk(sB[12], sB[13]); w.w = cvtpk(sB[14], sB[15]); pf[3] = __builtin_bit_cast(bf16x8, w); }
;       const char* Vl = lds + stage * 32768 + NK * 8192 + vrd;
;       if (FIXM) {
;         bf16x8 vf[4][NDV];
; #pragma unroll
;         for (int ks = 0; ks < 4; ++ks) {
; #pragma unroll
;           for (int d = 0; d < NDV; ++d) {
;             const s16x4 lo = __builtin_amdgcn_ds_read_tr16_b64_v4i16((LAS s16x4*)(Vl + ks * 2 * NDV * 512 + d * 512));
;             const s16x4 hi = __builtin_amdgcn_ds_read_tr16_b64_v4i16((LAS s16x4*)(Vl + ks * 2 * NDV * 512 + d * 512 + 256));
;             vf[ks][d] = __builtin_shufflevector(lo, hi, 0, 1, 2, 3, 4, 5, 6, 7);
;           }
;         }
; #pragma unroll
.Lds0_sk2:
	v_add_f32_e32 v164, v40, v164
	v_add_f32_e32 v164, v41, v164
	s_waitcnt lgkmcnt(12)
	v_mfma_f32_32x32x16_bf16 v[18:33], v[168:171], v[152:155], v[18:33]
	v_cvt_pk_bf16_f32 v156, v42, v43
	v_cvt_pk_bf16_f32 v157, v44, v45
	v_cvt_pk_bf16_f32 v158, v46, v47
	v_cvt_pk_bf16_f32 v159, v48, v49
	v_add_f32_e32 v115, v42, v115
	v_add_f32_e32 v115, v43, v115
	s_waitcnt lgkmcnt(10)
	v_mfma_f32_32x32x16_bf16 v[2:17], v[172:175], v[152:155], v[2:17]
	v_add_f32_e32 v164, v44, v164
	v_add_f32_e32 v164, v45, v164
	v_add_f32_e32 v164, v46, v164
	v_add_f32_e32 v164, v47, v164
	v_add_f32_e32 v164, v48, v164
	v_add_f32_e32 v164, v49, v164
	s_waitcnt lgkmcnt(8)
	v_mfma_f32_32x32x16_bf16 v[18:33], v[176:179], v[156:159], v[18:33]
	v_exp_f32_e32 v136, v136
	v_exp_f32_e32 v137, v137
	v_exp_f32_e32 v138, v138
	v_exp_f32_e32 v139, v139
	s_waitcnt lgkmcnt(6)
	v_mfma_f32_32x32x16_bf16 v[2:17], v[180:183], v[156:159], v[2:17]
	ds_read_b64_tr_b16 v[168:169], v98 offset:45056
	ds_read_b64_tr_b16 v[170:171], v98 offset:45312
	ds_read_b64_tr_b16 v[172:173], v98 offset:45568
	ds_read_b64_tr_b16 v[174:175], v98 offset:45824
	ds_read_b64_tr_b16 v[176:177], v98 offset:47104
	ds_read_b64_tr_b16 v[178:179], v98 offset:47360
	ds_read_b64_tr_b16 v[180:181], v98 offset:47616
	ds_read_b64_tr_b16 v[182:183], v98 offset:47872
	v_exp_f32_e32 v140, v140
	v_exp_f32_e32 v141, v141
	v_exp_f32_e32 v142, v142
	v_exp_f32_e32 v143, v143
	s_waitcnt lgkmcnt(13)
	v_mfma_f32_32x32x16_bf16 v[34:49], v[106:109], v[66:69], 0
	v_cvt_pk_bf16_f32 v160, v136, v137
	v_cvt_pk_bf16_f32 v161, v138, v139
	v_cvt_pk_bf16_f32 v162, v140, v141
	v_cvt_pk_bf16_f32 v163, v142, v143
	v_add_f32_e32 v115, v136, v115
	v_add_f32_e32 v115, v137, v115
	s_waitcnt lgkmcnt(12)
	v_mfma_f32_32x32x16_bf16 v[34:49], v[110:113], v[70:73], v[34:49]
	v_exp_f32_e32 v144, v144
	v_exp_f32_e32 v145, v145
	v_exp_f32_e32 v146, v146
	v_exp_f32_e32 v147, v147
	v_add_f32_e32 v164, v138, v164
	v_add_f32_e32 v164, v139, v164
	s_waitcnt lgkmcnt(11)
	v_mfma_f32_32x32x16_bf16 v[34:49], v[120:123], v[74:77], v[34:49]
	v_exp_f32_e32 v148, v148
	v_exp_f32_e32 v149, v149
	v_exp_f32_e32 v150, v150
	v_exp_f32_e32 v151, v151
	v_add_f32_e32 v115, v140, v115
	v_add_f32_e32 v115, v141, v115
	s_waitcnt lgkmcnt(10)
	v_mfma_f32_32x32x16_bf16 v[34:49], v[124:127], v[78:81], v[34:49]
	v_cvt_pk_bf16_f32 v184, v144, v145
	v_cvt_pk_bf16_f32 v185, v146, v147
	v_cvt_pk_bf16_f32 v186, v148, v149
	v_cvt_pk_bf16_f32 v187, v150, v151
	v_add_f32_e32 v164, v142, v164
	v_add_f32_e32 v164, v143, v164
	s_waitcnt lgkmcnt(6)
	v_mfma_f32_32x32x16_bf16 v[18:33], v[168:171], v[160:163], v[18:33]
	v_add_f32_e32 v115, v144, v115
	v_add_f32_e32 v115, v145, v115
	v_add_f32_e32 v115, v146, v115
	v_add_f32_e32 v115, v147, v115
	s_waitcnt lgkmcnt(4)
	v_mfma_f32_32x32x16_bf16 v[2:17], v[172:175], v[160:163], v[2:17]
	v_add_f32_e32 v164, v148, v164
	v_add_f32_e32 v164, v149, v164
	v_add_f32_e32 v164, v150, v164
	v_add_f32_e32 v164, v151, v164
	s_waitcnt lgkmcnt(2)
	v_mfma_f32_32x32x16_bf16 v[18:33], v[176:179], v[184:187], v[18:33]
	s_waitcnt lgkmcnt(0)
	s_waitcnt lgkmcnt(0)
	s_barrier
	v_mfma_f32_32x32x16_bf16 v[2:17], v[180:183], v[184:187], v[2:17]
	s_add_i32 s38, s38, 1
	s_cmp_ge_u32 s38, s96
	s_cbranch_scc1 .Lds0_done
	s_branch .Lds0_loop

; template <int DV, int NK, int MODE, bool FIXM, int GRP>
; DI void attn_job(char* lds_wg, const AttnJob& J) {
;     ...
;       if (FIXM) {
;         const float nm = -J.m_init;
; #pragma unroll
;         for (int i = 0; i < 16; ++i) { sA[i] = __builtin_amdgcn_exp2f(fmaf(sA[i], C, nm)); sB[i] = __builtin_amdgcn_exp2f(fmaf(sB[i], C, nm)); l += sA[i] + sB[i]; }
;       } else {
;       float mx = sA[0];
; #pragma unroll
;       for (int i = 1; i < 16; ++i) mx = fmaxf(mx, sA[i]);
; #pragma unroll
;       for (int i = 0; i < 16; ++i) mx = fmaxf(mx, sB[i]);
;       mx = swapmax(mx);
;       const float mn = fmaxf(m, mx * C);
;       const float alpha = __builtin_amdgcn_exp2f(m - mn);
;       m = mn;
;       float ps = 0.f;
; #pragma unroll
;       for (int i = 0; i < 16; ++i) { sA[i] = __builtin_amdgcn_exp2f(fmaf(sA[i], C, -mn)); sB[i] = __builtin_amdgcn_exp2f(fmaf(sB[i], C, -mn)); ps += sA[i] + sB[i]; }
;       l = l * alpha + ps;
; #pragma unroll
;       for (int d = 0; d < NDV; ++d)
; #pragma unroll
;         for (int i = 0; i < 16; ++i) O[d][i] *= alpha;
;       }
;       bf16x8 pf[4];
;       { u32x4 w;
;         w.x = cvtpk(sA[0], sA[1]); w.y = cvtpk(sA[2], sA[3]); w.z = cvtpk(sA[4], sA[5]); w.w = cvtpk(sA[6], sA[7]); pf[0] = __builtin_bit_cast(bf16x8, w);
;         w.x = cvtpk(sA[8], sA[9]); w.y = cvtpk(sA[10], sA[11]); w.z = cvtpk(sA[12], sA[13]); w.w = cvtpk(sA[14], sA[15]); pf[1] = __builtin_bit_cast(bf16x8, w);
;         w.x = cvtpk(sB[0], sB[1]); w.y = cvtpk(sB[2], sB[3]); w.z = cvtpk(sB[4], sB[5]); w.w = cvtpk(sB[6], sB[7]); pf[2] = __builtin_bit_cast(bf16x8, w);
;         w.x = cvtpk(sB[8], sB[9]); w.y = cvtpk(sB[10], sB[11]); w.z = cvtpk(sB[12], sB[13]); w.w = cvtpk(sB[14], sB[15]); pf[3] = __builtin_bit_cast(bf16x8, w); }
;       const char* Vl = lds + stage * 32768 + NK * 8192 + vrd;
;       if (FIXM) {
;         bf16x8 vf[4][NDV];
; #pragma unroll
;         for (int ks = 0; ks < 4; ++ks) {
; #pragma unroll
;           for (int d = 0; d < NDV; ++d) {
;             const s16x4 lo = __builtin_amdgcn_ds_read_tr16_b64_v4i16((LAS s16x4*)(Vl + ks * 2 * NDV * 512 + d * 512));
;             const s16x4 hi = __builtin_amdgcn_ds_read_tr16_b64_v4i16((LAS s16x4*)(Vl + ks * 2 * NDV * 512 + d * 512 + 256));
;             vf[ks][d] = __builtin_shufflevector(lo, hi, 0, 1, 2, 3, 4, 5, 6, 7);
;           }
;         }
; #pragma unroll
.Lds1_sk0:
	v_add_f32_e32 v164, v56, v164
	v_add_f32_e32 v164, v57, v164
	s_waitcnt lgkmcnt(12)
	v_mfma_f32_32x32x16_bf16 v[18:33], v[168:171], v[152:155], v[18:33]
	v_cvt_pk_bf16_f32 v156, v58, v59
	v_cvt_pk_bf16_f32 v157, v60, v61
	v_cvt_pk_bf16_f32 v158, v62, v63
	v_cvt_pk_bf16_f32 v159, v64, v65
	v_add_f32_e32 v115, v58, v115
	v_add_f32_e32 v115, v59, v115
	s_waitcnt lgkmcnt(10)
	v_mfma_f32_32x32x16_bf16 v[2:17], v[172:175], v[152:155], v[2:17]
	v_add_f32_e32 v164, v60, v164
	v_add_f32_e32 v164, v61, v164
	v_add_f32_e32 v164, v62, v164
	v_add_f32_e32 v164, v63, v164
	v_add_f32_e32 v164, v64, v164
	v_add_f32_e32 v164, v65, v164
	s_waitcnt lgkmcnt(8)
	v_mfma_f32_32x32x16_bf16 v[18:33], v[176:179], v[156:159], v[18:33]
	v_exp_f32_e32 v34, v34
	v_exp_f32_e32 v35, v35
	v_exp_f32_e32 v36, v36
	v_exp_f32_e32 v37, v37
	s_waitcnt lgkmcnt(6)
	v_mfma_f32_32x32x16_bf16 v[2:17], v[180:183], v[156:159], v[2:17]
	ds_read_b64_tr_b16 v[168:169], v98 offset:12288
	ds_read_b64_tr_b16 v[170:171], v98 offset:12544
	ds_read_b64_tr_b16 v[172:173], v98 offset:12800
	ds_read_b64_tr_b16 v[174:175], v98 offset:13056
	ds_read_b64_tr_b16 v[176:177], v98 offset:14336
	ds_read_b64_tr_b16 v[178:179], v98 offset:14592
	ds_read_b64_tr_b16 v[180:181], v98 offset:14848
	ds_read_b64_tr_b16 v[182:183], v98 offset:15104
	v_exp_f32_e32 v38, v38
	v_exp_f32_e32 v39, v39
	v_exp_f32_e32 v40, v40
	v_exp_f32_e32 v41, v41
	s_waitcnt lgkmcnt(13)
	v_mfma_f32_32x32x16_bf16 v[50:65], v[106:109], v[66:69], 0
	v_cvt_pk_bf16_f32 v160, v34, v35
	v_cvt_pk_bf16_f32 v161, v36, v37
	v_cvt_pk_bf16_f32 v162, v38, v39
	v_cvt_pk_bf16_f32 v163, v40, v41
	v_add_f32_e32 v115, v34, v115
	v_add_f32_e32 v115, v35, v115
	s_waitcnt lgkmcnt(12)
	v_mfma_f32_32x32x16_bf16 v[50:65], v[110:113], v[70:73], v[50:65]
	v_exp_f32_e32 v42, v42
	v_exp_f32_e32 v43, v43
	v_exp_f32_e32 v44, v44
	v_exp_f32_e32 v45, v45
	v_add_f32_e32 v164, v36, v164
	v_add_f32_e32 v164, v37, v164
	s_waitcnt lgkmcnt(11)
	v_mfma_f32_32x32x16_bf16 v[50:65], v[120:123], v[74:77], v[50:65]
	v_exp_f32_e32 v46, v46
	v_exp_f32_e32 v47, v47
	v_exp_f32_e32 v48, v48
	v_exp_f32_e32 v49, v49
	v_add_f32_e32 v115, v38, v115
	v_add_f32_e32 v115, v39, v115
	s_waitcnt lgkmcnt(10)
	v_mfma_f32_32x32x16_bf16 v[50:65], v[124:127], v[78:81], v[50:65]
	v_cvt_pk_bf16_f32 v184, v42, v43
	v_cvt_pk_bf16_f32 v185, v44, v45
	v_cvt_pk_bf16_f32 v186, v46, v47
	v_cvt_pk_bf16_f32 v187, v48, v49
	v_add_f32_e32 v164, v40, v164
	v_add_f32_e32 v164, v41, v164
	s_waitcnt lgkmcnt(6)
	v_mfma_f32_32x32x16_bf16 v[18:33], v[168:171], v[160:163], v[18:33]
	v_add_f32_e32 v115, v42, v115
	v_add_f32_e32 v115, v43, v115
	v_add_f32_e32 v115, v44, v115
	v_add_f32_e32 v115, v45, v115
	s_waitcnt lgkmcnt(4)
	v_mfma_f32_32x32x16_bf16 v[2:17], v[172:175], v[160:163], v[2:17]
	v_add_f32_e32 v164, v46, v164
	v_add_f32_e32 v164, v47, v164
	v_add_f32_e32 v164, v48, v164
	v_add_f32_e32 v164, v49, v164
	s_waitcnt lgkmcnt(2)
	v_mfma_f32_32x32x16_bf16 v[18:33], v[176:179], v[184:187], v[18:33]
	s_waitcnt lgkmcnt(0)
	s_waitcnt lgkmcnt(0)
	s_barrier
	v_mfma_f32_32x32x16_bf16 v[2:17], v[180:183], v[184:187], v[2:17]
	s_add_i32 s30, s30, 1
	s_cmp_ge_u32 s30, s96
	s_cbranch_scc1 .Lds1_done
	ds_read_b128 v[106:109], v0 offset:32768
	ds_read_b128 v[110:113], v102 offset:32768
	ds_read_b128 v[120:123], v103 offset:32768
	ds_read_b128 v[124:127], v104 offset:32768
	ds_read_b64_tr_b16 v[168:169], v98 offset:24576
	ds_read_b64_tr_b16 v[170:171], v98 offset:24832
	ds_read_b64_tr_b16 v[172:173], v98 offset:25088
	ds_read_b64_tr_b16 v[174:175], v98 offset:25344
	ds_read_b64_tr_b16 v[176:177], v98 offset:26624
	ds_read_b64_tr_b16 v[178:179], v98 offset:26880
	ds_read_b64_tr_b16 v[180:181], v98 offset:27136
	ds_read_b64_tr_b16 v[182:183], v98 offset:27392
	v_exp_f32_e32 v136, v136
	v_exp_f32_e32 v137, v137
	v_exp_f32_e32 v138, v138
	v_exp_f32_e32 v139, v139
	v_exp_f32_e32 v140, v140
	v_exp_f32_e32 v141, v141
	v_exp_f32_e32 v142, v142
	v_exp_f32_e32 v143, v143
	s_waitcnt lgkmcnt(11)
	v_mfma_f32_32x32x16_bf16 v[34:49], v[106:109], v[66:69], 0
	v_cvt_pk_bf16_f32 v152, v136, v137
	v_cvt_pk_bf16_f32 v153, v138, v139
	v_cvt_pk_bf16_f32 v154, v140, v141
	v_cvt_pk_bf16_f32 v155, v142, v143
	v_add_f32_e32 v115, v136, v115
	v_add_f32_e32 v115, v137, v115
	s_waitcnt lgkmcnt(10)
	v_mfma_f32_32x32x16_bf16 v[34:49], v[110:113], v[70:73], v[34:49]
	v_exp_f32_e32 v144, v144
	v_exp_f32_e32 v145, v145
	v_exp_f32_e32 v146, v146
	v_exp_f32_e32 v147, v147
	v_add_f32_e32 v164, v138, v164
	v_add_f32_e32 v164, v139, v164
	s_waitcnt lgkmcnt(9)
	v_mfma_f32_32x32x16_bf16 v[34:49], v[120:123], v[74:77], v[34:49]
	v_exp_f32_e32 v148, v148
	v_exp_f32_e32 v149, v149
	v_exp_f32_e32 v150, v150
	v_exp_f32_e32 v151, v151
	v_add_f32_e32 v115, v140, v115
	v_add_f32_e32 v115, v141, v115
	s_waitcnt lgkmcnt(8)
	v_mfma_f32_32x32x16_bf16 v[34:49], v[124:127], v[78:81], v[34:49]
	ds_read_b128 v[106:109], v0 offset:36864
	ds_read_b128 v[110:113], v102 offset:36864
	ds_read_b128 v[120:123], v103 offset:36864
	ds_read_b128 v[124:127], v104 offset:36864
	s_waitcnt vmcnt(0)
	ds_write_b128 v100, v[82:85] offset:0
	ds_write_b128 v165, v[86:89] offset:8192
	s_add_i32 s31, s30, 3
	s_cmp_lt_u32 s31, s96
	s_cbranch_scc0 .Lds1_sk1
	global_load_dwordx4 v[82:85], v[92:93], off offset:1024
	global_load_dwordx4 v[86:89], v[90:91], off offset:1280
	v_lshl_add_u64 v[92:93], v[92:93], 0, s[10:11]
	v_lshl_add_u64 v[90:91], v[90:91], 0, s[10:11]
; template <int DV, int NK, int MODE, bool FIXM, int GRP>
; DI void attn_job(char* lds_wg, const AttnJob& J) {
;     ...
;       if (FIXM) {
;         const float nm = -J.m_init;
; #pragma unroll
;         for (int i = 0; i < 16; ++i) { sA[i] = __builtin_amdgcn_exp2f(fmaf(sA[i], C, nm)); sB[i] = __builtin_amdgcn_exp2f(fmaf(sB[i], C, nm)); l += sA[i] + sB[i]; }
;       } else {
;       float mx = sA[0];
; #pragma unroll
;       for (int i = 1; i < 16; ++i) mx = fmaxf(mx, sA[i]);
; #pragma unroll
;       for (int i = 0; i < 16; ++i) mx = fmaxf(mx, sB[i]);
;       mx = swapmax(mx);
;       const float mn = fmaxf(m, mx * C);
;       const float alpha = __builtin_amdgcn_exp2f(m - mn);
;       m = mn;
;       float ps = 0.f;
; #pragma unroll
;       for (int i = 0; i < 16; ++i) { sA[i] = __builtin_amdgcn_exp2f(fmaf(sA[i], C, -mn)); sB[i] = __builtin_amdgcn_exp2f(fmaf(sB[i], C, -mn)); ps += sA[i] + sB[i]; }
;       l = l * alpha + ps;
; #pragma unroll
;       for (int d = 0; d < NDV; ++d)
; #pragma unroll
;         for (int i = 0; i < 16; ++i) O[d][i] *= alpha;
;       }
;       bf16x8 pf[4];
;       { u32x4 w;
;         w.x = cvtpk(sA[0], sA[1]); w.y = cvtpk(sA[2], sA[3]); w.z = cvtpk(sA[4], sA[5]); w.w = cvtpk(sA[6], sA[7]); pf[0] = __builtin_bit_cast(bf16x8, w);
;         w.x = cvtpk(sA[8], sA[9]); w.y = cvtpk(sA[10], sA[11]); w.z = cvtpk(sA[12], sA[13]); w.w = cvtpk(sA[14], sA[15]); pf[1] = __builtin_bit_cast(bf16x8, w);
;         w.x = cvtpk(sB[0], sB[1]); w.y = cvtpk(sB[2], sB[3]); w.z = cvtpk(sB[4], sB[5]); w.w = cvtpk(sB[6], sB[7]); pf[2] = __builtin_bit_cast(bf16x8, w);
;         w.x = cvtpk(sB[8], sB[9]); w.y = cvtpk(sB[10], sB[11]); w.z = cvtpk(sB[12], sB[13]); w.w = cvtpk(sB[14], sB[15]); pf[3] = __builtin_bit_cast(bf16x8, w); }
;       const char* Vl = lds + stage * 32768 + NK * 8192 + vrd;
;       if (FIXM) {
;         bf16x8 vf[4][NDV];
; #pragma unroll
;         for (int ks = 0; ks < 4; ++ks) {
; #pragma unroll
;           for (int d = 0; d < NDV; ++d) {
;             const s16x4 lo = __builtin_amdgcn_ds_read_tr16_b64_v4i16((LAS s16x4*)(Vl + ks * 2 * NDV * 512 + d * 512));
;             const s16x4 hi = __builtin_amdgcn_ds_read_tr16_b64_v4i16((LAS s16x4*)(Vl + ks * 2 * NDV * 512 + d * 512 + 256));
;             vf[ks][d] = __builtin_shufflevector(lo, hi, 0, 1, 2, 3, 4, 5, 6, 7);
;           }
;         }
; #pragma unroll
.Lds1_sk1:
	v_add_f32_e32 v164, v142, v164
	v_add_f32_e32 v164, v143, v164
	s_waitcnt lgkmcnt(12)
	v_mfma_f32_32x32x16_bf16 v[18:33], v[168:171], v[152:155], v[18:33]
	v_cvt_pk_bf16_f32 v156, v144, v145
	v_cvt_pk_bf16_f32 v157, v146, v147
	v_cvt_pk_bf16_f32 v158, v148, v149
	v_cvt_pk_bf16_f32 v159, v150, v151
	v_add_f32_e32 v115, v144, v115
	v_add_f32_e32 v115, v145, v115
	s_waitcnt lgkmcnt(10)
	v_mfma_f32_32x32x16_bf16 v[2:17], v[172:175], v[152:155], v[2:17]
	v_add_f32_e32 v164, v146, v164
	v_add_f32_e32 v164, v147, v164
	v_add_f32_e32 v164, v148, v164
	v_add_f32_e32 v164, v149, v164
	v_add_f32_e32 v164, v150, v164
	v_add_f32_e32 v164, v151, v164
	s_waitcnt lgkmcnt(8)
	v_mfma_f32_32x32x16_bf16 v[18:33], v[176:179], v[156:159], v[18:33]
	v_exp_f32_e32 v50, v50
	v_exp_f32_e32 v51, v51
	v_exp_f32_e32 v52, v52
	v_exp_f32_e32 v53, v53
	s_waitcnt lgkmcnt(6)
	v_mfma_f32_32x32x16_bf16 v[2:17], v[180:183], v[156:159], v[2:17]
	ds_read_b64_tr_b16 v[168:169], v98 offset:28672
	ds_read_b64_tr_b16 v[170:171], v98 offset:28928
	ds_read_b64_tr_b16 v[172:173], v98 offset:29184
	ds_read_b64_tr_b16 v[174:175], v98 offset:29440
	ds_read_b64_tr_b16 v[176:177], v98 offset:30720
	ds_read_b64_tr_b16 v[178:179], v98 offset:30976
	ds_read_b64_tr_b16 v[180:181], v98 offset:31232
	ds_read_b64_tr_b16 v[182:183], v98 offset:31488
	v_exp_f32_e32 v54, v54
	v_exp_f32_e32 v55, v55
	v_exp_f32_e32 v56, v56
	v_exp_f32_e32 v57, v57
	s_waitcnt lgkmcnt(13)
	v_mfma_f32_32x32x16_bf16 v[136:151], v[106:109], v[66:69], 0
	v_cvt_pk_bf16_f32 v160, v50, v51
	v_cvt_pk_bf16_f32 v161, v52, v53
	v_cvt_pk_bf16_f32 v162, v54, v55
	v_cvt_pk_bf16_f32 v163, v56, v57
	v_add_f32_e32 v115, v50, v115
	v_add_f32_e32 v115, v51, v115
	s_waitcnt lgkmcnt(12)
	v_mfma_f32_32x32x16_bf16 v[136:151], v[110:113], v[70:73], v[136:151]
	v_exp_f32_e32 v58, v58
	v_exp_f32_e32 v59, v59
	v_exp_f32_e32 v60, v60
	v_exp_f32_e32 v61, v61
	v_add_f32_e32 v164, v52, v164
	v_add_f32_e32 v164, v53, v164
	s_waitcnt lgkmcnt(11)
	v_mfma_f32_32x32x16_bf16 v[136:151], v[120:123], v[74:77], v[136:151]
	v_exp_f32_e32 v62, v62
	v_exp_f32_e32 v63, v63
	v_exp_f32_e32 v64, v64
	v_exp_f32_e32 v65, v65
	v_add_f32_e32 v115, v54, v115
	v_add_f32_e32 v115, v55, v115
	s_waitcnt lgkmcnt(10)
	v_mfma_f32_32x32x16_bf16 v[136:151], v[124:127], v[78:81], v[136:151]
	v_cvt_pk_bf16_f32 v184, v58, v59
	v_cvt_pk_bf16_f32 v185, v60, v61
	v_cvt_pk_bf16_f32 v186, v62, v63
	v_cvt_pk_bf16_f32 v187, v64, v65
	v_add_f32_e32 v164, v56, v164
	v_add_f32_e32 v164, v57, v164
	s_waitcnt lgkmcnt(6)
	v_mfma_f32_32x32x16_bf16 v[18:33], v[168:171], v[160:163], v[18:33]
	v_add_f32_e32 v115, v58, v115
	v_add_f32_e32 v115, v59, v115
	v_add_f32_e32 v115, v60, v115
	v_add_f32_e32 v115, v61, v115
	s_waitcnt lgkmcnt(4)
	v_mfma_f32_32x32x16_bf16 v[2:17], v[172:175], v[160:163], v[2:17]
	v_add_f32_e32 v164, v62, v164
	v_add_f32_e32 v164, v63, v164
	v_add_f32_e32 v164, v64, v164
	v_add_f32_e32 v164, v65, v164
	s_waitcnt lgkmcnt(2)
	v_mfma_f32_32x32x16_bf16 v[18:33], v[176:179], v[184:187], v[18:33]
	s_waitcnt lgkmcnt(0)
	s_waitcnt lgkmcnt(0)
	s_barrier
	v_mfma_f32_32x32x16_bf16 v[2:17], v[180:183], v[184:187], v[2:17]
	s_add_i32 s30, s30, 1
	s_cmp_ge_u32 s30, s96
	s_cbranch_scc1 .Lds1_done
	ds_read_b128 v[106:109], v0 offset:0
	ds_read_b128 v[110:113], v102 offset:0
	ds_read_b128 v[120:123], v103 offset:0
	ds_read_b128 v[124:127], v104 offset:0
	ds_read_b64_tr_b16 v[168:169], v98 offset:40960
	ds_read_b64_tr_b16 v[170:171], v98 offset:41216
	ds_read_b64_tr_b16 v[172:173], v98 offset:41472
	ds_read_b64_tr_b16 v[174:175], v98 offset:41728
	ds_read_b64_tr_b16 v[176:177], v98 offset:43008
	ds_read_b64_tr_b16 v[178:179], v98 offset:43264
	ds_read_b64_tr_b16 v[180:181], v98 offset:43520
	ds_read_b64_tr_b16 v[182:183], v98 offset:43776
	v_exp_f32_e32 v34, v34
	v_exp_f32_e32 v35, v35
	v_exp_f32_e32 v36, v36
	v_exp_f32_e32 v37, v37
	v_exp_f32_e32 v38, v38
	v_exp_f32_e32 v39, v39
	v_exp_f32_e32 v40, v40
	v_exp_f32_e32 v41, v41
	s_waitcnt lgkmcnt(11)
	v_mfma_f32_32x32x16_bf16 v[50:65], v[106:109], v[66:69], 0
	v_cvt_pk_bf16_f32 v152, v34, v35
	v_cvt_pk_bf16_f32 v153, v36, v37
	v_cvt_pk_bf16_f32 v154, v38, v39
	v_cvt_pk_bf16_f32 v155, v40, v41
	v_add_f32_e32 v115, v34, v115
	v_add_f32_e32 v115, v35, v115
	s_waitcnt lgkmcnt(10)
	v_mfma_f32_32x32x16_bf16 v[50:65], v[110:113], v[70:73], v[50:65]
	v_exp_f32_e32 v42, v42
	v_exp_f32_e32 v43, v43
	v_exp_f32_e32 v44, v44
	v_exp_f32_e32 v45, v45
	v_add_f32_e32 v164, v36, v164
	v_add_f32_e32 v164, v37, v164
	s_waitcnt lgkmcnt(9)
	v_mfma_f32_32x32x16_bf16 v[50:65], v[120:123], v[74:77], v[50:65]
	v_exp_f32_e32 v46, v46
	v_exp_f32_e32 v47, v47
	v_exp_f32_e32 v48, v48
	v_exp_f32_e32 v49, v49
	v_add_f32_e32 v115, v38, v115
	v_add_f32_e32 v115, v39, v115
	s_waitcnt lgkmcnt(8)
	v_mfma_f32_32x32x16_bf16 v[50:65], v[124:127], v[78:81], v[50:65]
	ds_read_b128 v[106:109], v0 offset:4096
	ds_read_b128 v[110:113], v102 offset:4096
	ds_read_b128 v[120:123], v103 offset:4096
	ds_read_b128 v[124:127], v104 offset:4096
	s_waitcnt vmcnt(0)
	ds_write_b128 v100, v[82:85] offset:16384
	ds_write_b128 v165, v[86:89] offset:24576
	s_add_i32 s31, s30, 3
	s_cmp_lt_u32 s31, s96
	s_cbranch_scc0 .Lds1_sk2
	global_load_dwordx4 v[82:85], v[92:93], off offset:1024
	global_load_dwordx4 v[86:89], v[90:91], off offset:1280
	v_lshl_add_u64 v[92:93], v[92:93], 0, s[10:11]
	v_lshl_add_u64 v[90:91], v[90:91], 0, s[10:11]
; template <int DV, int NK, int MODE, bool FIXM, int GRP>
; DI void attn_job(char* lds_wg, const AttnJob& J) {
;     ...
;       if (FIXM) {
;         const float nm = -J.m_init;
; #pragma unroll
;         for (int i = 0; i < 16; ++i) { sA[i] = __builtin_amdgcn_exp2f(fmaf(sA[i], C, nm)); sB[i] = __builtin_amdgcn_exp2f(fmaf(sB[i], C, nm)); l += sA[i] + sB[i]; }
;       } else {
;       float mx = sA[0];
; #pragma unroll
;       for (int i = 1; i < 16; ++i) mx = fmaxf(mx, sA[i]);
; #pragma unroll
;       for (int i = 0; i < 16; ++i) mx = fmaxf(mx, sB[i]);
;       mx = swapmax(mx);
;       const float mn = fmaxf(m, mx * C);
;       const float alpha = __builtin_amdgcn_exp2f(m - mn);
;       m = mn;
;       float ps = 0.f;
; #pragma unroll
;       for (int i = 0; i < 16; ++i) { sA[i] = __builtin_amdgcn_exp2f(fmaf(sA[i], C, -mn)); sB[i] = __builtin_amdgcn_exp2f(fmaf(sB[i], C, -mn)); ps += sA[i] + sB[i]; }
;       l = l * alpha + ps;
; #pragma unroll
;       for (int d = 0; d < NDV; ++d)
; #pragma unroll
;         for (int i = 0; i < 16; ++i) O[d][i] *= alpha;
;       }
;       bf16x8 pf[4];
;       { u32x4 w;
;         w.x = cvtpk(sA[0], sA[1]); w.y = cvtpk(sA[2], sA[3]); w.z = cvtpk(sA[4], sA[5]); w.w = cvtpk(sA[6], sA[7]); pf[0] = __builtin_bit_cast(bf16x8, w);
;         w.x = cvtpk(sA[8], sA[9]); w.y = cvtpk(sA[10], sA[11]); w.z = cvtpk(sA[12], sA[13]); w.w = cvtpk(sA[14], sA[15]); pf[1] = __builtin_bit_cast(bf16x8, w);
;         w.x = cvtpk(sB[0], sB[1]); w.y = cvtpk(sB[2], sB[3]); w.z = cvtpk(sB[4], sB[5]); w.w = cvtpk(sB[6], sB[7]); pf[2] = __builtin_bit_cast(bf16x8, w);
;         w.x = cvtpk(sB[8], sB[9]); w.y = cvtpk(sB[10], sB[11]); w.z = cvtpk(sB[12], sB[13]); w.w = cvtpk(sB[14], sB[15]); pf[3] = __builtin_bit_cast(bf16x8, w); }
;       const char* Vl = lds + stage * 32768 + NK * 8192 + vrd;
;       if (FIXM) {
;         bf16x8 vf[4][NDV];
; #pragma unroll
;         for (int ks = 0; ks < 4; ++ks) {
; #pragma unroll
;           for (int d = 0; d < NDV; ++d) {
;             const s16x4 lo = __builtin_amdgcn_ds_read_tr16_b64_v4i16((LAS s16x4*)(Vl + ks * 2 * NDV * 512 + d * 512));
;             const s16x4 hi = __builtin_amdgcn_ds_read_tr16_b64_v4i16((LAS s16x4*)(Vl + ks * 2 * NDV * 512 + d * 512 + 256));
;             vf[ks][d] = __builtin_shufflevector(lo, hi, 0, 1, 2, 3, 4, 5, 6, 7);
;           }
;         }
; #pragma unroll
.Lds1_sk2:
	v_add_f32_e32 v164, v40, v164
	v_add_f32_e32 v164, v41, v164
	s_waitcnt lgkmcnt(12)
	v_mfma_f32_32x32x16_bf16 v[18:33], v[168:171], v[152:155], v[18:33]
	v_cvt_pk_bf16_f32 v156, v42, v43
	v_cvt_pk_bf16_f32 v157, v44, v45
	v_cvt_pk_bf16_f32 v158, v46, v47
	v_cvt_pk_bf16_f32 v159, v48, v49
	v_add_f32_e32 v115, v42, v115
	v_add_f32_e32 v115, v43, v115
	s_waitcnt lgkmcnt(10)
	v_mfma_f32_32x32x16_bf16 v[2:17], v[172:175], v[152:155], v[2:17]
	v_add_f32_e32 v164, v44, v164
	v_add_f32_e32 v164, v45, v164
	v_add_f32_e32 v164, v46, v164
	v_add_f32_e32 v164, v47, v164
	v_add_f32_e32 v164, v48, v164
	v_add_f32_e32 v164, v49, v164
	s_waitcnt lgkmcnt(8)
	v_mfma_f32_32x32x16_bf16 v[18:33], v[176:179], v[156:159], v[18:33]
	v_exp_f32_e32 v136, v136
	v_exp_f32_e32 v137, v137
	v_exp_f32_e32 v138, v138
	v_exp_f32_e32 v139, v139
	s_waitcnt lgkmcnt(6)
	v_mfma_f32_32x32x16_bf16 v[2:17], v[180:183], v[156:159], v[2:17]
	ds_read_b64_tr_b16 v[168:169], v98 offset:45056
	ds_read_b64_tr_b16 v[170:171], v98 offset:45312
	ds_read_b64_tr_b16 v[172:173], v98 offset:45568
	ds_read_b64_tr_b16 v[174:175], v98 offset:45824
	ds_read_b64_tr_b16 v[176:177], v98 offset:47104
	ds_read_b64_tr_b16 v[178:179], v98 offset:47360
	ds_read_b64_tr_b16 v[180:181], v98 offset:47616
	ds_read_b64_tr_b16 v[182:183], v98 offset:47872
	v_exp_f32_e32 v140, v140
	v_exp_f32_e32 v141, v141
	v_exp_f32_e32 v142, v142
	v_exp_f32_e32 v143, v143
	s_waitcnt lgkmcnt(13)
	v_mfma_f32_32x32x16_bf16 v[34:49], v[106:109], v[66:69], 0
	v_cvt_pk_bf16_f32 v160, v136, v137
	v_cvt_pk_bf16_f32 v161, v138, v139
	v_cvt_pk_bf16_f32 v162, v140, v141
	v_cvt_pk_bf16_f32 v163, v142, v143
	v_add_f32_e32 v115, v136, v115
	v_add_f32_e32 v115, v137, v115
	s_waitcnt lgkmcnt(12)
	v_mfma_f32_32x32x16_bf16 v[34:49], v[110:113], v[70:73], v[34:49]
	v_exp_f32_e32 v144, v144
	v_exp_f32_e32 v145, v145
	v_exp_f32_e32 v146, v146
	v_exp_f32_e32 v147, v147
	v_add_f32_e32 v164, v138, v164
	v_add_f32_e32 v164, v139, v164
	s_waitcnt lgkmcnt(11)
	v_mfma_f32_32x32x16_bf16 v[34:49], v[120:123], v[74:77], v[34:49]
	v_exp_f32_e32 v148, v148
	v_exp_f32_e32 v149, v149
	v_exp_f32_e32 v150, v150
	v_exp_f32_e32 v151, v151
	v_add_f32_e32 v115, v140, v115
	v_add_f32_e32 v115, v141, v115
	s_waitcnt lgkmcnt(10)
	v_mfma_f32_32x32x16_bf16 v[34:49], v[124:127], v[78:81], v[34:49]
	v_cvt_pk_bf16_f32 v184, v144, v145
	v_cvt_pk_bf16_f32 v185, v146, v147
	v_cvt_pk_bf16_f32 v186, v148, v149
	v_cvt_pk_bf16_f32 v187, v150, v151
	v_add_f32_e32 v164, v142, v164
	v_add_f32_e32 v164, v143, v164
	s_waitcnt lgkmcnt(6)
	v_mfma_f32_32x32x16_bf16 v[18:33], v[168:171], v[160:163], v[18:33]
	v_add_f32_e32 v115, v144, v115
	v_add_f32_e32 v115, v145, v115
	v_add_f32_e32 v115, v146, v115
	v_add_f32_e32 v115, v147, v115
	s_waitcnt lgkmcnt(4)
	v_mfma_f32_32x32x16_bf16 v[2:17], v[172:175], v[160:163], v[2:17]
	v_add_f32_e32 v164, v148, v164
	v_add_f32_e32 v164, v149, v164
	v_add_f32_e32 v164, v150, v164
	v_add_f32_e32 v164, v151, v164
	s_waitcnt lgkmcnt(2)
	v_mfma_f32_32x32x16_bf16 v[18:33], v[176:179], v[184:187], v[18:33]
	s_waitcnt lgkmcnt(0)
	s_waitcnt lgkmcnt(0)
	s_barrier
	v_mfma_f32_32x32x16_bf16 v[2:17], v[180:183], v[184:187], v[2:17]
	s_add_i32 s30, s30, 1
	s_cmp_ge_u32 s30, s96
	s_cbranch_scc1 .Lds1_done
	s_branch .Lds1_loop
